# ATTN far-tile interleaved MFMA/exp schedule + grid barriers 2..10 with one polled cross-XCC counter
# baseline (speedup 1.0000x reference)
.LBB0_955:
	s_add_i32 s35, s15, -2
	s_lshl_b32 s5, s34, 13
	s_cmp_lt_u32 s15, s27
	s_cselect_b32 s10, s15, s29
	s_lshl_b64 s[6:7], s[10:11], 16
	s_waitcnt vmcnt(0)
	v_lshrrev_b32_e32 v3, v1, v138
	v_lshl_add_u64 v[6:7], v[116:117], 0, s[6:7]
	v_lshl_add_u64 v[8:9], v[118:119], 0, s[6:7]
	s_add_i32 s6, s5, 0xffffe000
	v_lshlrev_b32_e32 v3, 4, v3
	s_cmp_lg_u32 s34, 0
	v_and_b32_e32 v4, 0xf0f0f0f0, v3
	v_lshrrev_b32_e32 v3, v1, v139
	s_cselect_b32 s6, s6, 0x4000
	v_lshlrev_b32_e32 v3, 4, v3
	s_add_i32 s6, s6, 0
	v_and_b32_e32 v3, 0xf0f0f0f0, v3
	s_add_i32 s6, s20, s6
	s_waitcnt lgkmcnt(0)
	s_barrier
	s_add_i32 s7, s6, 0x6000
	s_mov_b32 m0, s6
	global_load_lds_dwordx4 v[6:7], off
	s_mov_b32 m0, s7
	global_load_lds_dwordx4 v[8:9], off
	s_add_i32 s6, s15, -1
	s_cmp_lt_u32 s35, 63
	s_cselect_b32 s10, s6, 63
	s_lshl_b64 s[6:7], s[10:11], 15
	v_lshl_add_u64 v[6:7], v[136:137], 0, s[6:7]
	global_load_dwordx2 v[138:139], v[6:7], off
	s_cmp_gt_u32 s35, s28
	s_cbranch_scc1 .LBB0_954
	s_cmp_lt_u32 s33, s14
	s_cbranch_scc1 .Lattn_fast
	v_add_u32_sdwa v5, v4, s25 dst_sel:DWORD dst_unused:UNUSED_PAD src0_sel:BYTE_0 src1_sel:DWORD
	ds_read_b128 v[66:69], v5
	v_add_u32_sdwa v5, v3, s25 dst_sel:DWORD dst_unused:UNUSED_PAD src0_sel:BYTE_0 src1_sel:DWORD
	v_add_u32_e32 v14, s5, v140
	ds_read_b128 v[82:85], v5
	v_add_u32_sdwa v5, v4, s25 dst_sel:DWORD dst_unused:UNUSED_PAD src0_sel:BYTE_1 src1_sel:DWORD
	ds_read_b128 v[6:9], v14
	ds_read_b128 v[10:13], v14 offset:512
	ds_read_b128 v[70:73], v5
	v_add_u32_sdwa v5, v4, s25 dst_sel:DWORD dst_unused:UNUSED_PAD src0_sel:BYTE_2 src1_sel:DWORD
	v_add_u32_sdwa v4, v4, s25 dst_sel:DWORD dst_unused:UNUSED_PAD src0_sel:BYTE_3 src1_sel:DWORD
	ds_read_b128 v[78:81], v4
	v_add_u32_sdwa v4, v3, s25 dst_sel:DWORD dst_unused:UNUSED_PAD src0_sel:BYTE_1 src1_sel:DWORD
	ds_read_b128 v[86:89], v4
	v_add_u32_sdwa v4, v3, s25 dst_sel:DWORD dst_unused:UNUSED_PAD src0_sel:BYTE_2 src1_sel:DWORD
	v_add_u32_sdwa v3, v3, s25 dst_sel:DWORD dst_unused:UNUSED_PAD src0_sel:BYTE_3 src1_sel:DWORD
	ds_read_b128 v[74:77], v5
	ds_read_b128 v[90:93], v4
	ds_read_b128 v[94:97], v3
	s_waitcnt lgkmcnt(2)
	v_mfma_f32_32x32x16_bf16 v[66:81], v[6:9], v[110:113], v[66:81]
	s_cmp_lt_u32 s33, s14
	s_waitcnt lgkmcnt(0)
	v_mfma_f32_32x32x16_bf16 v[82:97], v[10:13], v[110:113], v[82:97]
	ds_read_b128 v[4:7], v14 offset:2048
	ds_read_b128 v[8:11], v14 offset:2560
	s_waitcnt lgkmcnt(1)
	v_mfma_f32_32x32x16_bf16 v[66:81], v[4:7], v[98:101], v[66:81]
	s_waitcnt lgkmcnt(0)
	v_mfma_f32_32x32x16_bf16 v[82:97], v[8:11], v[98:101], v[82:97]
	ds_read_b128 v[4:7], v14 offset:4096
	ds_read_b128 v[8:11], v14 offset:4608
	s_waitcnt lgkmcnt(1)
	v_mfma_f32_32x32x16_bf16 v[66:81], v[4:7], v[102:105], v[66:81]
	s_waitcnt lgkmcnt(0)
	v_mfma_f32_32x32x16_bf16 v[82:97], v[8:11], v[102:105], v[82:97]
	ds_read_b128 v[4:7], v14 offset:6144
	ds_read_b128 v[8:11], v14 offset:6656
	s_waitcnt lgkmcnt(1)
	v_mfma_f32_32x32x16_bf16 v[66:81], v[4:7], v[106:109], v[66:81]
	s_waitcnt lgkmcnt(0)
	v_mfma_f32_32x32x16_bf16 v[82:97], v[8:11], v[106:109], v[82:97]
	s_cbranch_scc1 .LBB0_953
	v_add_u32_e32 v3, s31, v148
	v_add_u32_e32 v4, 0x149fc, v3
	v_add_u32_e32 v6, 0x1497c, v3
	v_add_u32_e32 v8, 0x149f4, v3
	ds_read2_b32 v[4:5], v4 offset1:1
	ds_read2_b32 v[6:7], v6 offset1:1
	ds_read2_b32 v[8:9], v8 offset1:1
	v_add_u32_e32 v10, 0x14974, v3
	v_add_u32_e32 v12, 0x14954, v3
	s_waitcnt lgkmcnt(2)
	v_pk_add_f32 v[66:67], v[66:67], v[4:5] op_sel:[0,1] op_sel_hi:[1,0]
	s_waitcnt lgkmcnt(1)
	v_pk_add_f32 v[82:83], v[82:83], v[6:7] op_sel:[0,1] op_sel_hi:[1,0]
	s_waitcnt lgkmcnt(0)
	v_pk_add_f32 v[68:69], v[68:69], v[8:9] op_sel:[0,1] op_sel_hi:[1,0]
	v_add_u32_e32 v4, 0x149dc, v3
	v_add_u32_e32 v6, 0x1495c, v3
	v_add_u32_e32 v8, 0x149d4, v3
	ds_read2_b32 v[10:11], v10 offset1:1
	ds_read2_b32 v[4:5], v4 offset1:1
	ds_read2_b32 v[6:7], v6 offset1:1
	ds_read2_b32 v[8:9], v8 offset1:1
	ds_read2_b32 v[12:13], v12 offset1:1
	s_waitcnt lgkmcnt(3)
	v_pk_add_f32 v[70:71], v[70:71], v[4:5] op_sel:[0,1] op_sel_hi:[1,0]
	s_waitcnt lgkmcnt(2)
	v_pk_add_f32 v[86:87], v[86:87], v[6:7] op_sel:[0,1] op_sel_hi:[1,0]
	s_waitcnt lgkmcnt(1)
	v_pk_add_f32 v[72:73], v[72:73], v[8:9] op_sel:[0,1] op_sel_hi:[1,0]
	v_add_u32_e32 v4, 0x149bc, v3
	v_add_u32_e32 v6, 0x1493c, v3
	v_add_u32_e32 v8, 0x149b4, v3
	ds_read2_b32 v[4:5], v4 offset1:1
	ds_read2_b32 v[6:7], v6 offset1:1
	ds_read2_b32 v[8:9], v8 offset1:1
	v_pk_add_f32 v[84:85], v[84:85], v[10:11] op_sel:[0,1] op_sel_hi:[1,0]
	v_add_u32_e32 v10, 0x14934, v3
	s_waitcnt lgkmcnt(2)
	v_pk_add_f32 v[74:75], v[74:75], v[4:5] op_sel:[0,1] op_sel_hi:[1,0]
	s_waitcnt lgkmcnt(1)
	v_pk_add_f32 v[90:91], v[90:91], v[6:7] op_sel:[0,1] op_sel_hi:[1,0]
	s_waitcnt lgkmcnt(0)
	v_pk_add_f32 v[76:77], v[76:77], v[8:9] op_sel:[0,1] op_sel_hi:[1,0]
	v_add_u32_e32 v4, 0x1499c, v3
	v_add_u32_e32 v6, 0x1491c, v3
	v_add_u32_e32 v8, 0x14994, v3
	v_pk_add_f32 v[88:89], v[88:89], v[12:13] op_sel:[0,1] op_sel_hi:[1,0]
	ds_read2_b32 v[10:11], v10 offset1:1
	v_add_u32_e32 v3, 0x14914, v3
	ds_read2_b32 v[4:5], v4 offset1:1
	ds_read2_b32 v[6:7], v6 offset1:1
	ds_read2_b32 v[8:9], v8 offset1:1
	ds_read2_b32 v[12:13], v3 offset1:1
	s_waitcnt lgkmcnt(3)
	v_pk_add_f32 v[78:79], v[78:79], v[4:5] op_sel:[0,1] op_sel_hi:[1,0]
	v_pk_add_f32 v[92:93], v[92:93], v[10:11] op_sel:[0,1] op_sel_hi:[1,0]
	s_waitcnt lgkmcnt(2)
	v_pk_add_f32 v[94:95], v[94:95], v[6:7] op_sel:[0,1] op_sel_hi:[1,0]
	s_waitcnt lgkmcnt(1)
	v_pk_add_f32 v[80:81], v[80:81], v[8:9] op_sel:[0,1] op_sel_hi:[1,0]
	s_waitcnt lgkmcnt(0)
	v_pk_add_f32 v[96:97], v[96:97], v[12:13] op_sel:[0,1] op_sel_hi:[1,0]
	s_branch .LBB0_953
